# rwkv_out prefetch no longer waited on at issue; rwkv scan waves prio 2 over co-resident S5 waves; workgroup barrier instead of grid barrier between rwkv_out and GLU/attention phase
# speedup vs baseline: 1.0232x; 1.0127x over previous
; #define LAS __attribute__((address_space(3)))
; #define WAVE_SYNC() asm volatile("s_waitcnt lgkmcnt(0)" ::: "memory")
; __device__ __forceinline__ void rwkv_out(const Params& p, int l, int wave, int lane, LAS unsigned char* lds) {
;     ...
;         for (int bt = 0; bt < 8; ++bt) {
;             float yc[4], bc[4], gc[4];
; #pragma unroll
;             for (int q = 0; q < 4; ++q) { qb[q * 64 + lane] = q4[q]; yc[q] = y4[q]; bc[q] = b4[q]; gc[q] = g4[q]; }
;             if (bt + 1 < 8) {
; #pragma unroll
;                 for (int q = 0; q < 4; ++q) { const size_t o = (size_t)(m0 + (bt + 1) * 4 + q) * 768; q4[q] = (QQ + o)[ch]; y4[q] = (YL + o)[ch]; b4[q] = BF2F((BON + o)[ch]); g4[q] = BF2F((LR + (size_t)(m0 + (bt + 1) * 4 + q) * 2304 + 1536)[ch]); }
;             }
;             WAVE_SYNC();
; #pragma unroll
;             for (int q = 0; q < 4; ++q) {
;                 const LAS f32x4* Q4 = (const LAS f32x4*)(qb + q * 64);
;                 f32x2 a0 = {0.f, 0.f}, a1 = {0.f, 0.f};
; #pragma unroll
;                 for (int j = 0; j < 16; ++j) { const f32x4 v = Q4[j]; a0 += s[2 * j] * (f32x2){v.x, v.y}; a1 += s[2 * j + 1] * (f32x2){v.z, v.w}; }
.LBB0_92:
	v_lshl_add_u64 v[66:67], s[18:19], 0, v[80:81]
	s_mov_b32 s7, 0x29003000
	v_add_co_u32_e32 v68, vcc, s7, v66
	s_mov_b32 s7, 0x22e03000
	s_nop 0
	v_addc_co_u32_e32 v69, vcc, 0, v67, vcc
	v_add_co_u32_e32 v70, vcc, s7, v66
	ds_write2st64_b32 v94, v101, v102 offset1:1
	ds_write2st64_b32 v94, v103, v104 offset0:2 offset1:3
	v_addc_co_u32_e32 v71, vcc, 0, v67, vcc
	v_lshl_add_u64 v[92:93], s[18:19], 0, v[82:83]
	s_mov_b32 s7, 0x24601000
	v_mov_b32_e32 v109, v100
	v_mov_b32_e32 v108, v99
	global_load_dword v101, v[68:69], off
	global_load_dword v100, v[70:71], off
	global_load_dword v102, v[68:69], off offset:3072
	global_load_dword v99, v[70:71], off offset:3072
	v_add_co_u32_e32 v68, vcc, s7, v92
	v_lshl_add_u64 v[110:111], s[18:19], 0, v[78:79]
	s_nop 0
	v_addc_co_u32_e32 v69, vcc, 0, v93, vcc
	global_load_ushort v144, v[68:69], off offset:3584
	s_nop 0
	global_load_ushort v145, v[68:69], off offset:2048
	s_mov_b32 s7, 0x20a06000
	v_mov_b32_e32 v106, v98
	v_mov_b32_e32 v105, v97
	v_mov_b32_e32 v107, s11
	s_add_i32 s6, s6, -1
	v_lshl_add_u64 v[82:83], v[82:83], 0, s[20:21]
	s_cmp_eq_u32 s6, 0
	v_add_co_u32_e32 v68, vcc, s7, v110
	s_mov_b32 s7, 0x20a05000
	s_nop 0
	v_addc_co_u32_e32 v69, vcc, 0, v111, vcc
	global_load_ushort v146, v[68:69], off offset:1536
	v_add_co_u32_e32 v68, vcc, s7, v110
	s_mov_b32 s7, 0x29004000
	s_nop 0
	v_addc_co_u32_e32 v69, vcc, 0, v111, vcc
	global_load_ushort v147, v[68:69], off offset:1024
	v_add_co_u32_e32 v68, vcc, s7, v66
	s_mov_b32 s7, 0x22e04000
	s_nop 0
	v_addc_co_u32_e32 v69, vcc, 0, v67, vcc
	global_load_dword v103, v[68:69], off offset:2048
	v_add_co_u32_e32 v68, vcc, s7, v66
	s_mov_b32 s7, 0x29005000
	s_nop 0
	v_addc_co_u32_e32 v69, vcc, 0, v67, vcc
	global_load_dword v98, v[68:69], off offset:2048
	v_add_co_u32_e32 v68, vcc, s7, v66
	s_mov_b32 s7, 0x22e05000
	s_nop 0
	v_addc_co_u32_e32 v69, vcc, 0, v67, vcc
	v_add_co_u32_e32 v66, vcc, s7, v66
	s_mov_b32 s7, 0x24602000
	s_nop 0
	v_addc_co_u32_e32 v67, vcc, 0, v67, vcc
	global_load_dword v104, v[68:69], off offset:1024
	global_load_dword v97, v[66:67], off offset:1024
	v_add_co_u32_e32 v66, vcc, s7, v92
	s_mov_b32 s7, 0x20a08000
	s_nop 0
	v_addc_co_u32_e32 v67, vcc, 0, v93, vcc
	global_load_ushort v148, v[66:67], off offset:2560
	s_nop 0
	global_load_ushort v149, v[66:67], off offset:1024
	v_add_co_u32_e32 v68, vcc, s7, v110
	s_mov_b32 s7, 0x20a07000
	s_nop 0
	v_addc_co_u32_e32 v69, vcc, 0, v111, vcc
	global_load_ushort v150, v[68:69], off offset:2560
	v_add_co_u32_e32 v68, vcc, s7, v110
	s_nop 1
	v_addc_co_u32_e32 v69, vcc, 0, v111, vcc
	global_load_ushort v151, v[68:69], off offset:2048
	s_waitcnt lgkmcnt(0)
	ds_read_b128 v[110:113], v107
	ds_read_b128 v[114:117], v107 offset:16
	ds_read_b128 v[118:121], v107 offset:32
	ds_read_b128 v[122:125], v107 offset:48
	s_waitcnt lgkmcnt(3)
	v_pk_fma_f32 v[92:93], v[42:43], v[110:111], 0 op_sel_hi:[1,1,0]
	v_pk_fma_f32 v[110:111], v[44:45], v[112:113], 0 op_sel_hi:[1,1,0]
	s_waitcnt lgkmcnt(2)
	v_pk_fma_f32 v[92:93], v[48:49], v[114:115], v[92:93]
	v_pk_fma_f32 v[110:111], v[50:51], v[116:117], v[110:111]
	s_waitcnt lgkmcnt(1)
	v_pk_fma_f32 v[92:93], v[54:55], v[118:119], v[92:93]
	v_pk_fma_f32 v[110:111], v[58:59], v[120:121], v[110:111]
	s_waitcnt lgkmcnt(0)
	v_pk_fma_f32 v[92:93], v[60:61], v[122:123], v[92:93]
	v_pk_fma_f32 v[114:115], v[62:63], v[124:125], v[110:111]
	ds_read_b128 v[110:113], v107 offset:64
	s_waitcnt lgkmcnt(0)
	v_pk_fma_f32 v[92:93], v[56:57], v[110:111], v[92:93]
	v_pk_fma_f32 v[114:115], v[64:65], v[112:113], v[114:115]
	ds_read_b128 v[110:113], v107 offset:80
	s_waitcnt lgkmcnt(0)
	v_pk_fma_f32 v[92:93], v[46:47], v[110:111], v[92:93]
	v_pk_fma_f32 v[114:115], v[52:53], v[112:113], v[114:115]
	ds_read_b128 v[110:113], v107 offset:96
	s_waitcnt lgkmcnt(0)
	v_pk_fma_f32 v[92:93], v[38:39], v[110:111], v[92:93]
	v_pk_fma_f32 v[114:115], v[40:41], v[112:113], v[114:115]
	ds_read_b128 v[110:113], v107 offset:112
	s_waitcnt lgkmcnt(0)
	v_pk_fma_f32 v[92:93], v[28:29], v[110:111], v[92:93]
	v_pk_fma_f32 v[114:115], v[30:31], v[112:113], v[114:115]
	ds_read_b128 v[110:113], v107 offset:128
	s_waitcnt lgkmcnt(0)
	v_pk_fma_f32 v[92:93], v[34:35], v[110:111], v[92:93]
	v_pk_fma_f32 v[114:115], v[36:37], v[112:113], v[114:115]
	ds_read_b128 v[110:113], v107 offset:144
	s_waitcnt lgkmcnt(0)
	v_pk_fma_f32 v[92:93], v[26:27], v[110:111], v[92:93]
	v_pk_fma_f32 v[114:115], v[32:33], v[112:113], v[114:115]
	ds_read_b128 v[110:113], v107 offset:160
	s_waitcnt lgkmcnt(0)
	v_pk_fma_f32 v[92:93], v[20:21], v[110:111], v[92:93]
	v_pk_fma_f32 v[114:115], v[24:25], v[112:113], v[114:115]
	ds_read_b128 v[110:113], v107 offset:176
	s_waitcnt lgkmcnt(0)
	v_pk_fma_f32 v[92:93], v[14:15], v[110:111], v[92:93]
	v_pk_fma_f32 v[114:115], v[16:17], v[112:113], v[114:115]
	ds_read_b128 v[110:113], v107 offset:192
	s_waitcnt lgkmcnt(0)
	v_pk_fma_f32 v[92:93], v[18:19], v[110:111], v[92:93]
	v_pk_fma_f32 v[114:115], v[22:23], v[112:113], v[114:115]
	ds_read_b128 v[110:113], v107 offset:208
	s_waitcnt lgkmcnt(0)
	v_pk_fma_f32 v[92:93], v[10:11], v[110:111], v[92:93]
	v_pk_fma_f32 v[114:115], v[12:13], v[112:113], v[114:115]
	ds_read_b128 v[110:113], v107 offset:224
	s_waitcnt lgkmcnt(0)
	v_pk_fma_f32 v[92:93], v[6:7], v[110:111], v[92:93]
	v_pk_fma_f32 v[114:115], v[8:9], v[112:113], v[114:115]
	ds_read_b128 v[110:113], v107 offset:240
	s_waitcnt lgkmcnt(0)
; __device__ __forceinline__ unsigned cvt_pk_bf16(float lo, float hi) { unsigned r; asm volatile("v_cvt_pk_bf16_f32 %0, %1, %2" : "=v"(r) : "v"(lo), "v"(hi)); return r; }
; #define LAS __attribute__((address_space(3)))
; __device__ __forceinline__ void rwkv_out(const Params& p, int l, int wave, int lane, LAS unsigned char* lds) {
;     ...
;             for (int q = 0; q < 4; ++q) {
;                 const LAS f32x4* Q4 = (const LAS f32x4*)(qb + q * 64);
;                 f32x2 a0 = {0.f, 0.f}, a1 = {0.f, 0.f};
; #pragma unroll
;                 for (int j = 0; j < 16; ++j) { const f32x4 v = Q4[j]; a0 += s[2 * j] * (f32x2){v.x, v.y}; a1 += s[2 * j + 1] * (f32x2){v.z, v.w}; }
;                 const float yo = yc[q] + (a0.x + a0.y) + (a1.x + a1.y);
;                 const float mean = wave_sum(yo) * (1.0f / 64.0f); const float d = yo - mean; const float var = wave_sum(d * d) * (1.0f / 64.0f);
;                 const float o = (d * rsqrtf(var + 64e-5f) * gnw + gnb + bc[q]) * gc[q];
;                 YCAT[(size_t)(m0 + bt * 4 + q) * DM + ch] = (bf16_t)(cvt_pk_bf16(o, 0.f) & 0xffffu);
	v_pk_fma_f32 v[92:93], v[4:5], v[110:111], v[92:93]
	v_pk_fma_f32 v[110:111], v[2:3], v[112:113], v[114:115]
	v_mov_b32_e32 v113, v92
	v_mov_b32_e32 v112, v110
	v_mov_b32_e32 v92, v111
	v_pk_add_f32 v[92:93], v[112:113], v[92:93]
	s_nop 0
	v_add_f32_e32 v93, v109, v93
	v_add_f32_e32 v109, v92, v93
	s_nop 1
	v_add_f32_dpp v92, v109, v109 quad_perm:[1,0,3,2] row_mask:0xf bank_mask:0xf bound_ctrl:1
	s_nop 1
	v_add_f32_dpp v92, v92, v92 quad_perm:[2,3,0,1] row_mask:0xf bank_mask:0xf bound_ctrl:1
	s_nop 1
	v_add_f32_dpp v92, v92, v92 row_ror:4 row_mask:0xf bank_mask:0xf bound_ctrl:1
	s_nop 1
	v_add_f32_dpp v92, v92, v92 row_ror:8 row_mask:0xf bank_mask:0xf bound_ctrl:1
	s_nop 0
	v_readlane_b32 s7, v92, 16
	v_readlane_b32 s16, v92, 48
	v_readlane_b32 s14, v92, 0
	v_readlane_b32 s15, v92, 32
	v_mov_b32_e32 v92, s7
	v_mov_b32_e32 v93, s16
	v_pk_add_f32 v[92:93], s[14:15], v[92:93]
	s_nop 0
	v_add_f32_e32 v92, v92, v93
	v_fmac_f32_e32 v109, 0xbc800000, v92
	v_mul_f32_e32 v92, v109, v109
	s_nop 1
	v_mov_b32_dpp v92, v92 quad_perm:[1,0,3,2] row_mask:0xf bank_mask:0xf bound_ctrl:1
	v_fmac_f32_e32 v92, v109, v109
	s_nop 1
	v_add_f32_dpp v92, v92, v92 quad_perm:[2,3,0,1] row_mask:0xf bank_mask:0xf bound_ctrl:1
	s_nop 1
	v_add_f32_dpp v92, v92, v92 row_ror:4 row_mask:0xf bank_mask:0xf bound_ctrl:1
	s_nop 1
	v_add_f32_dpp v92, v92, v92 row_ror:8 row_mask:0xf bank_mask:0xf bound_ctrl:1
	s_nop 0
	v_readlane_b32 s7, v92, 16
	v_readlane_b32 s16, v92, 48
	v_readlane_b32 s14, v92, 0
	v_readlane_b32 s15, v92, 32
	v_mov_b32_e32 v92, s7
	v_mov_b32_e32 v93, s16
	v_pk_add_f32 v[92:93], s[14:15], v[92:93]
	s_mov_b32 s7, 0x16201000
	v_add_f32_e32 v92, v92, v93
	v_fmamk_f32 v92, v92, 0x3c800000, v185
	v_cmp_gt_f32_e32 vcc, s3, v92
	v_mul_f32_e32 v93, 0x4b800000, v92
	s_nop 0
	v_cndmask_b32_e32 v92, v92, v93, vcc
	v_rsq_f32_e32 v92, v92
	s_nop 0
	v_mul_f32_e32 v93, 0x45800000, v92
	v_cndmask_b32_e32 v92, v92, v93, vcc
	v_mul_f32_e32 v92, v109, v92
	v_fma_f32 v92, v95, v92, v96
	v_add_f32_e32 v89, v89, v92
	v_lshl_add_u64 v[92:93], s[18:19], 0, v[76:77]
	v_add_co_u32_e32 v126, vcc, s7, v92
	v_mul_f32_e32 v89, v91, v89
	s_nop 0
	v_addc_co_u32_e32 v127, vcc, 0, v93, vcc
	v_cvt_pk_bf16_f32 v89, v89, v137
	global_store_short v[126:127], v89, off offset:-4096
	ds_read_b128 v[110:113], v107 offset:256
	ds_read_b128 v[114:117], v107 offset:272
	ds_read_b128 v[118:121], v107 offset:288
	ds_read_b128 v[122:125], v107 offset:304
	s_waitcnt lgkmcnt(3)
	v_pk_fma_f32 v[110:111], v[42:43], v[110:111], 0 op_sel_hi:[1,1,0]
	v_pk_fma_f32 v[112:113], v[44:45], v[112:113], 0 op_sel_hi:[1,1,0]
	s_waitcnt lgkmcnt(2)
	v_pk_fma_f32 v[110:111], v[48:49], v[114:115], v[110:111]
	v_pk_fma_f32 v[112:113], v[50:51], v[116:117], v[112:113]
	s_waitcnt lgkmcnt(1)
	v_pk_fma_f32 v[110:111], v[54:55], v[118:119], v[110:111]
	v_pk_fma_f32 v[112:113], v[58:59], v[120:121], v[112:113]
	s_waitcnt lgkmcnt(0)
	v_pk_fma_f32 v[114:115], v[60:61], v[122:123], v[110:111]
	v_pk_fma_f32 v[116:117], v[62:63], v[124:125], v[112:113]
	ds_read_b128 v[110:113], v107 offset:320
	s_waitcnt lgkmcnt(0)
	v_pk_fma_f32 v[114:115], v[56:57], v[110:111], v[114:115]
	v_pk_fma_f32 v[116:117], v[64:65], v[112:113], v[116:117]
	ds_read_b128 v[110:113], v107 offset:336
	s_waitcnt lgkmcnt(0)
	v_pk_fma_f32 v[114:115], v[46:47], v[110:111], v[114:115]
	v_pk_fma_f32 v[116:117], v[52:53], v[112:113], v[116:117]
	ds_read_b128 v[110:113], v107 offset:352
	s_waitcnt lgkmcnt(0)
	v_pk_fma_f32 v[114:115], v[38:39], v[110:111], v[114:115]
	v_pk_fma_f32 v[116:117], v[40:41], v[112:113], v[116:117]
	ds_read_b128 v[110:113], v107 offset:368
	s_waitcnt lgkmcnt(0)
	v_pk_fma_f32 v[114:115], v[28:29], v[110:111], v[114:115]
	v_pk_fma_f32 v[116:117], v[30:31], v[112:113], v[116:117]
	ds_read_b128 v[110:113], v107 offset:384
	s_waitcnt lgkmcnt(0)
	v_pk_fma_f32 v[114:115], v[34:35], v[110:111], v[114:115]
	v_pk_fma_f32 v[116:117], v[36:37], v[112:113], v[116:117]
	ds_read_b128 v[110:113], v107 offset:400
	s_waitcnt lgkmcnt(0)
	v_pk_fma_f32 v[114:115], v[26:27], v[110:111], v[114:115]
	v_pk_fma_f32 v[116:117], v[32:33], v[112:113], v[116:117]
	ds_read_b128 v[110:113], v107 offset:416
	s_waitcnt lgkmcnt(0)
	v_pk_fma_f32 v[114:115], v[20:21], v[110:111], v[114:115]
	v_pk_fma_f32 v[116:117], v[24:25], v[112:113], v[116:117]
	ds_read_b128 v[110:113], v107 offset:432
	s_waitcnt lgkmcnt(0)
	v_pk_fma_f32 v[114:115], v[14:15], v[110:111], v[114:115]
	v_pk_fma_f32 v[116:117], v[16:17], v[112:113], v[116:117]
	ds_read_b128 v[110:113], v107 offset:448
	s_waitcnt lgkmcnt(0)
	v_pk_fma_f32 v[114:115], v[18:19], v[110:111], v[114:115]
	v_pk_fma_f32 v[116:117], v[22:23], v[112:113], v[116:117]
	ds_read_b128 v[110:113], v107 offset:464
	s_waitcnt lgkmcnt(0)
	v_pk_fma_f32 v[114:115], v[10:11], v[110:111], v[114:115]
	v_pk_fma_f32 v[116:117], v[12:13], v[112:113], v[116:117]
	ds_read_b128 v[110:113], v107 offset:480
	s_waitcnt lgkmcnt(0)
	v_pk_fma_f32 v[114:115], v[6:7], v[110:111], v[114:115]
	v_pk_fma_f32 v[116:117], v[8:9], v[112:113], v[116:117]
	ds_read_b128 v[110:113], v107 offset:496
	s_waitcnt lgkmcnt(0)
; __device__ __forceinline__ unsigned cvt_pk_bf16(float lo, float hi) { unsigned r; asm volatile("v_cvt_pk_bf16_f32 %0, %1, %2" : "=v"(r) : "v"(lo), "v"(hi)); return r; }
; #define LAS __attribute__((address_space(3)))
; __device__ __forceinline__ void rwkv_out(const Params& p, int l, int wave, int lane, LAS unsigned char* lds) {
;     ...
;             for (int q = 0; q < 4; ++q) {
;                 const LAS f32x4* Q4 = (const LAS f32x4*)(qb + q * 64);
;                 f32x2 a0 = {0.f, 0.f}, a1 = {0.f, 0.f};
; #pragma unroll
;                 for (int j = 0; j < 16; ++j) { const f32x4 v = Q4[j]; a0 += s[2 * j] * (f32x2){v.x, v.y}; a1 += s[2 * j + 1] * (f32x2){v.z, v.w}; }
;                 const float yo = yc[q] + (a0.x + a0.y) + (a1.x + a1.y);
;                 const float mean = wave_sum(yo) * (1.0f / 64.0f); const float d = yo - mean; const float var = wave_sum(d * d) * (1.0f / 64.0f);
;                 const float o = (d * rsqrtf(var + 64e-5f) * gnw + gnb + bc[q]) * gc[q];
;                 YCAT[(size_t)(m0 + bt * 4 + q) * DM + ch] = (bf16_t)(cvt_pk_bf16(o, 0.f) & 0xffffu);
	v_pk_fma_f32 v[110:111], v[4:5], v[110:111], v[114:115]
	v_pk_fma_f32 v[112:113], v[2:3], v[112:113], v[116:117]
	v_mov_b32_e32 v115, v110
	v_mov_b32_e32 v114, v112
	v_mov_b32_e32 v110, v113
	v_pk_add_f32 v[110:111], v[114:115], v[110:111]
	s_nop 0
	v_add_f32_e32 v89, v108, v111
	v_add_f32_e32 v89, v110, v89
	s_nop 1
	v_add_f32_dpp v91, v89, v89 quad_perm:[1,0,3,2] row_mask:0xf bank_mask:0xf bound_ctrl:1
	s_nop 1
	v_add_f32_dpp v91, v91, v91 quad_perm:[2,3,0,1] row_mask:0xf bank_mask:0xf bound_ctrl:1
	s_nop 1
	v_add_f32_dpp v91, v91, v91 row_ror:4 row_mask:0xf bank_mask:0xf bound_ctrl:1
	s_nop 1
	v_add_f32_dpp v91, v91, v91 row_ror:8 row_mask:0xf bank_mask:0xf bound_ctrl:1
	s_nop 0
	v_readlane_b32 s7, v91, 16
	v_readlane_b32 s16, v91, 48
	v_readlane_b32 s14, v91, 0
	v_readlane_b32 s15, v91, 32
	v_mov_b32_e32 v108, s7
	v_mov_b32_e32 v109, s16
	v_pk_add_f32 v[108:109], s[14:15], v[108:109]
	s_nop 0
	v_add_f32_e32 v91, v108, v109
	v_fmac_f32_e32 v89, 0xbc800000, v91
	v_mul_f32_e32 v91, v89, v89
	s_nop 1
	v_mov_b32_dpp v91, v91 quad_perm:[1,0,3,2] row_mask:0xf bank_mask:0xf bound_ctrl:1
	v_fmac_f32_e32 v91, v89, v89
	s_nop 1
	v_add_f32_dpp v91, v91, v91 quad_perm:[2,3,0,1] row_mask:0xf bank_mask:0xf bound_ctrl:1
	s_nop 1
	v_add_f32_dpp v91, v91, v91 row_ror:4 row_mask:0xf bank_mask:0xf bound_ctrl:1
	s_nop 1
	v_add_f32_dpp v91, v91, v91 row_ror:8 row_mask:0xf bank_mask:0xf bound_ctrl:1
	s_nop 0
	v_readlane_b32 s7, v91, 16
	v_readlane_b32 s16, v91, 48
	v_readlane_b32 s14, v91, 0
	v_readlane_b32 s15, v91, 32
	v_mov_b32_e32 v108, s7
	v_mov_b32_e32 v109, s16
	v_pk_add_f32 v[108:109], s[14:15], v[108:109]
	s_nop 0
	v_add_f32_e32 v91, v108, v109
	v_fmamk_f32 v91, v91, 0x3c800000, v185
	v_cmp_gt_f32_e32 vcc, s3, v91
	v_mul_f32_e32 v108, 0x4b800000, v91
	s_nop 0
	v_cndmask_b32_e32 v91, v91, v108, vcc
	v_rsq_f32_e32 v91, v91
	s_nop 0
	v_mul_f32_e32 v108, 0x45800000, v91
	v_cndmask_b32_e32 v91, v91, v108, vcc
	v_mul_f32_e32 v89, v89, v91
	v_fma_f32 v89, v95, v89, v96
	v_add_f32_e32 v88, v88, v89
	v_mul_f32_e32 v88, v90, v88
	v_cvt_pk_bf16_f32 v88, v88, v137
	global_store_short v[126:127], v88, off
	ds_read_b128 v[88:91], v107 offset:512
	ds_read_b128 v[108:111], v107 offset:528
	ds_read_b128 v[112:115], v107 offset:544
	ds_read_b128 v[116:119], v107 offset:560
	s_waitcnt lgkmcnt(3)
	v_pk_fma_f32 v[88:89], v[42:43], v[88:89], 0 op_sel_hi:[1,1,0]
	v_pk_fma_f32 v[90:91], v[44:45], v[90:91], 0 op_sel_hi:[1,1,0]
	s_waitcnt lgkmcnt(2)
	v_pk_fma_f32 v[88:89], v[48:49], v[108:109], v[88:89]
	v_pk_fma_f32 v[90:91], v[50:51], v[110:111], v[90:91]
	s_waitcnt lgkmcnt(1)
	v_pk_fma_f32 v[88:89], v[54:55], v[112:113], v[88:89]
	v_pk_fma_f32 v[90:91], v[58:59], v[114:115], v[90:91]
	s_waitcnt lgkmcnt(0)
	v_pk_fma_f32 v[108:109], v[60:61], v[116:117], v[88:89]
	v_pk_fma_f32 v[110:111], v[62:63], v[118:119], v[90:91]
	ds_read_b128 v[88:91], v107 offset:576
	s_waitcnt lgkmcnt(0)
	v_pk_fma_f32 v[108:109], v[56:57], v[88:89], v[108:109]
	v_pk_fma_f32 v[110:111], v[64:65], v[90:91], v[110:111]
	ds_read_b128 v[88:91], v107 offset:592
	s_waitcnt lgkmcnt(0)
	v_pk_fma_f32 v[108:109], v[46:47], v[88:89], v[108:109]
	v_pk_fma_f32 v[110:111], v[52:53], v[90:91], v[110:111]
	ds_read_b128 v[88:91], v107 offset:608
	s_waitcnt lgkmcnt(0)
	v_pk_fma_f32 v[108:109], v[38:39], v[88:89], v[108:109]
	v_pk_fma_f32 v[110:111], v[40:41], v[90:91], v[110:111]
	ds_read_b128 v[88:91], v107 offset:624
	s_waitcnt lgkmcnt(0)
	v_pk_fma_f32 v[108:109], v[28:29], v[88:89], v[108:109]
	v_pk_fma_f32 v[110:111], v[30:31], v[90:91], v[110:111]
	ds_read_b128 v[88:91], v107 offset:640
	s_waitcnt lgkmcnt(0)
	v_pk_fma_f32 v[108:109], v[34:35], v[88:89], v[108:109]
	v_pk_fma_f32 v[110:111], v[36:37], v[90:91], v[110:111]
	ds_read_b128 v[88:91], v107 offset:656
	s_waitcnt lgkmcnt(0)
	v_pk_fma_f32 v[108:109], v[26:27], v[88:89], v[108:109]
	v_pk_fma_f32 v[110:111], v[32:33], v[90:91], v[110:111]
	ds_read_b128 v[88:91], v107 offset:672
	s_waitcnt lgkmcnt(0)
	v_pk_fma_f32 v[108:109], v[20:21], v[88:89], v[108:109]
	v_pk_fma_f32 v[110:111], v[24:25], v[90:91], v[110:111]
	ds_read_b128 v[88:91], v107 offset:688
	s_waitcnt lgkmcnt(0)
	v_pk_fma_f32 v[108:109], v[14:15], v[88:89], v[108:109]
	v_pk_fma_f32 v[110:111], v[16:17], v[90:91], v[110:111]
	ds_read_b128 v[88:91], v107 offset:704
	s_waitcnt lgkmcnt(0)
	v_pk_fma_f32 v[108:109], v[18:19], v[88:89], v[108:109]
	v_pk_fma_f32 v[110:111], v[22:23], v[90:91], v[110:111]
	ds_read_b128 v[88:91], v107 offset:720
	s_waitcnt lgkmcnt(0)
	v_pk_fma_f32 v[108:109], v[10:11], v[88:89], v[108:109]
	v_pk_fma_f32 v[110:111], v[12:13], v[90:91], v[110:111]
	ds_read_b128 v[88:91], v107 offset:736
	s_waitcnt lgkmcnt(0)
	v_pk_fma_f32 v[108:109], v[6:7], v[88:89], v[108:109]
	v_pk_fma_f32 v[110:111], v[8:9], v[90:91], v[110:111]
	ds_read_b128 v[88:91], v107 offset:752
	s_waitcnt lgkmcnt(0)
; __device__ __forceinline__ unsigned cvt_pk_bf16(float lo, float hi) { unsigned r; asm volatile("v_cvt_pk_bf16_f32 %0, %1, %2" : "=v"(r) : "v"(lo), "v"(hi)); return r; }
; #define LAS __attribute__((address_space(3)))
; __device__ __forceinline__ void rwkv_out(const Params& p, int l, int wave, int lane, LAS unsigned char* lds) {
;     ...
;             for (int q = 0; q < 4; ++q) {
;                 const LAS f32x4* Q4 = (const LAS f32x4*)(qb + q * 64);
;                 f32x2 a0 = {0.f, 0.f}, a1 = {0.f, 0.f};
; #pragma unroll
;                 for (int j = 0; j < 16; ++j) { const f32x4 v = Q4[j]; a0 += s[2 * j] * (f32x2){v.x, v.y}; a1 += s[2 * j + 1] * (f32x2){v.z, v.w}; }
;                 const float yo = yc[q] + (a0.x + a0.y) + (a1.x + a1.y);
;                 const float mean = wave_sum(yo) * (1.0f / 64.0f); const float d = yo - mean; const float var = wave_sum(d * d) * (1.0f / 64.0f);
;                 const float o = (d * rsqrtf(var + 64e-5f) * gnw + gnb + bc[q]) * gc[q];
;                 YCAT[(size_t)(m0 + bt * 4 + q) * DM + ch] = (bf16_t)(cvt_pk_bf16(o, 0.f) & 0xffffu);
	v_pk_fma_f32 v[88:89], v[4:5], v[88:89], v[108:109]
	v_pk_fma_f32 v[90:91], v[2:3], v[90:91], v[110:111]
	v_mov_b32_e32 v109, v88
	v_mov_b32_e32 v108, v90
	v_mov_b32_e32 v88, v91
	v_pk_add_f32 v[88:89], v[108:109], v[88:89]
	s_nop 0
	v_add_f32_e32 v89, v106, v89
	v_add_f32_e32 v90, v88, v89
	s_nop 1
	v_add_f32_dpp v88, v90, v90 quad_perm:[1,0,3,2] row_mask:0xf bank_mask:0xf bound_ctrl:1
	s_nop 1
	v_add_f32_dpp v88, v88, v88 quad_perm:[2,3,0,1] row_mask:0xf bank_mask:0xf bound_ctrl:1
	s_nop 1
	v_add_f32_dpp v88, v88, v88 row_ror:4 row_mask:0xf bank_mask:0xf bound_ctrl:1
	s_nop 1
	v_add_f32_dpp v88, v88, v88 row_ror:8 row_mask:0xf bank_mask:0xf bound_ctrl:1
	s_nop 0
	v_readlane_b32 s7, v88, 16
	v_readlane_b32 s16, v88, 48
	v_readlane_b32 s14, v88, 0
	v_readlane_b32 s15, v88, 32
	v_mov_b32_e32 v88, s7
	v_mov_b32_e32 v89, s16
	v_pk_add_f32 v[88:89], s[14:15], v[88:89]
	s_nop 0
	v_add_f32_e32 v88, v88, v89
	v_fmac_f32_e32 v90, 0xbc800000, v88
	v_mul_f32_e32 v88, v90, v90
	s_nop 1
	v_mov_b32_dpp v88, v88 quad_perm:[1,0,3,2] row_mask:0xf bank_mask:0xf bound_ctrl:1
	v_fmac_f32_e32 v88, v90, v90
	s_nop 1
	v_add_f32_dpp v88, v88, v88 quad_perm:[2,3,0,1] row_mask:0xf bank_mask:0xf bound_ctrl:1
	s_nop 1
	v_add_f32_dpp v88, v88, v88 row_ror:4 row_mask:0xf bank_mask:0xf bound_ctrl:1
	s_nop 1
	v_add_f32_dpp v88, v88, v88 row_ror:8 row_mask:0xf bank_mask:0xf bound_ctrl:1
	s_nop 0
	v_readlane_b32 s7, v88, 16
	v_readlane_b32 s16, v88, 48
	v_readlane_b32 s14, v88, 0
	v_readlane_b32 s15, v88, 32
	v_mov_b32_e32 v88, s7
	v_mov_b32_e32 v89, s16
	v_pk_add_f32 v[88:89], s[14:15], v[88:89]
	s_mov_b32 s7, 0x16202000
	v_add_f32_e32 v88, v88, v89
	v_fmamk_f32 v88, v88, 0x3c800000, v185
	v_cmp_gt_f32_e32 vcc, s3, v88
	v_mul_f32_e32 v89, 0x4b800000, v88
	s_nop 0
	v_cndmask_b32_e32 v88, v88, v89, vcc
	v_rsq_f32_e32 v88, v88
	s_nop 0
	v_mul_f32_e32 v89, 0x45800000, v88
	v_cndmask_b32_e32 v88, v88, v89, vcc
	v_mul_f32_e32 v88, v90, v88
	v_fma_f32 v88, v95, v88, v96
	v_add_f32_e32 v85, v85, v88
	v_add_co_u32_e32 v88, vcc, s7, v92
	v_mul_f32_e32 v85, v87, v85
	s_nop 0
	v_addc_co_u32_e32 v89, vcc, 0, v93, vcc
	v_cvt_pk_bf16_f32 v85, v85, v137
	global_store_short v[88:89], v85, off
	ds_read_b128 v[88:91], v107 offset:768
	ds_read_b128 v[108:111], v107 offset:784
	ds_read_b128 v[112:115], v107 offset:800
	ds_read_b128 v[116:119], v107 offset:816
	s_waitcnt lgkmcnt(3)
	v_pk_fma_f32 v[88:89], v[42:43], v[88:89], 0 op_sel_hi:[1,1,0]
	v_pk_fma_f32 v[90:91], v[44:45], v[90:91], 0 op_sel_hi:[1,1,0]
	s_waitcnt lgkmcnt(2)
	v_pk_fma_f32 v[88:89], v[48:49], v[108:109], v[88:89]
	v_pk_fma_f32 v[90:91], v[50:51], v[110:111], v[90:91]
	s_waitcnt lgkmcnt(1)
	v_pk_fma_f32 v[88:89], v[54:55], v[112:113], v[88:89]
	v_pk_fma_f32 v[90:91], v[58:59], v[114:115], v[90:91]
	s_waitcnt lgkmcnt(0)
	v_pk_fma_f32 v[108:109], v[60:61], v[116:117], v[88:89]
	v_pk_fma_f32 v[110:111], v[62:63], v[118:119], v[90:91]
	ds_read_b128 v[88:91], v107 offset:832
	s_waitcnt lgkmcnt(0)
	v_pk_fma_f32 v[108:109], v[56:57], v[88:89], v[108:109]
	v_pk_fma_f32 v[110:111], v[64:65], v[90:91], v[110:111]
	ds_read_b128 v[88:91], v107 offset:848
	s_waitcnt lgkmcnt(0)
	v_pk_fma_f32 v[108:109], v[46:47], v[88:89], v[108:109]
	v_pk_fma_f32 v[110:111], v[52:53], v[90:91], v[110:111]
	ds_read_b128 v[88:91], v107 offset:864
	s_waitcnt lgkmcnt(0)
	v_pk_fma_f32 v[108:109], v[38:39], v[88:89], v[108:109]
	v_pk_fma_f32 v[110:111], v[40:41], v[90:91], v[110:111]
	ds_read_b128 v[88:91], v107 offset:880
	s_waitcnt lgkmcnt(0)
	v_pk_fma_f32 v[108:109], v[28:29], v[88:89], v[108:109]
	v_pk_fma_f32 v[110:111], v[30:31], v[90:91], v[110:111]
	ds_read_b128 v[88:91], v107 offset:896
	s_waitcnt lgkmcnt(0)
	v_pk_fma_f32 v[108:109], v[34:35], v[88:89], v[108:109]
	v_pk_fma_f32 v[110:111], v[36:37], v[90:91], v[110:111]
	ds_read_b128 v[88:91], v107 offset:912
	s_waitcnt lgkmcnt(0)
	v_pk_fma_f32 v[108:109], v[26:27], v[88:89], v[108:109]
	v_pk_fma_f32 v[110:111], v[32:33], v[90:91], v[110:111]
	ds_read_b128 v[88:91], v107 offset:928
	s_waitcnt lgkmcnt(0)
	v_pk_fma_f32 v[108:109], v[20:21], v[88:89], v[108:109]
	v_pk_fma_f32 v[110:111], v[24:25], v[90:91], v[110:111]
	ds_read_b128 v[88:91], v107 offset:944
	s_waitcnt lgkmcnt(0)
	v_pk_fma_f32 v[108:109], v[14:15], v[88:89], v[108:109]
	v_pk_fma_f32 v[110:111], v[16:17], v[90:91], v[110:111]
	ds_read_b128 v[88:91], v107 offset:960
	s_waitcnt lgkmcnt(0)
	v_pk_fma_f32 v[108:109], v[18:19], v[88:89], v[108:109]
	v_pk_fma_f32 v[110:111], v[22:23], v[90:91], v[110:111]
	ds_read_b128 v[88:91], v107 offset:976
	s_waitcnt lgkmcnt(0)
	v_pk_fma_f32 v[108:109], v[10:11], v[88:89], v[108:109]
	v_pk_fma_f32 v[110:111], v[12:13], v[90:91], v[110:111]
	ds_read_b128 v[88:91], v107 offset:992
	s_waitcnt lgkmcnt(0)
	v_pk_fma_f32 v[108:109], v[6:7], v[88:89], v[108:109]
	v_pk_fma_f32 v[110:111], v[8:9], v[90:91], v[110:111]
	ds_read_b128 v[88:91], v107 offset:1008
	s_waitcnt lgkmcnt(0)
; __device__ __forceinline__ unsigned cvt_pk_bf16(float lo, float hi) { unsigned r; asm volatile("v_cvt_pk_bf16_f32 %0, %1, %2" : "=v"(r) : "v"(lo), "v"(hi)); return r; }
; #define LAS __attribute__((address_space(3)))
; #define WAVE_SYNC() asm volatile("s_waitcnt lgkmcnt(0)" ::: "memory")
; __device__ __forceinline__ void rwkv_out(const Params& p, int l, int wave, int lane, LAS unsigned char* lds) {
;     ...
;         for (int bt = 0; bt < 8; ++bt) {
;             float yc[4], bc[4], gc[4];
; #pragma unroll
;             for (int q = 0; q < 4; ++q) { qb[q * 64 + lane] = q4[q]; yc[q] = y4[q]; bc[q] = b4[q]; gc[q] = g4[q]; }
;             if (bt + 1 < 8) {
; #pragma unroll
;                 for (int q = 0; q < 4; ++q) { const size_t o = (size_t)(m0 + (bt + 1) * 4 + q) * 768; q4[q] = (QQ + o)[ch]; y4[q] = (YL + o)[ch]; b4[q] = BF2F((BON + o)[ch]); g4[q] = BF2F((LR + (size_t)(m0 + (bt + 1) * 4 + q) * 2304 + 1536)[ch]); }
;             }
;             WAVE_SYNC();
; #pragma unroll
;             for (int q = 0; q < 4; ++q) {
;                 const LAS f32x4* Q4 = (const LAS f32x4*)(qb + q * 64);
;                 f32x2 a0 = {0.f, 0.f}, a1 = {0.f, 0.f};
; #pragma unroll
;                 for (int j = 0; j < 16; ++j) { const f32x4 v = Q4[j]; a0 += s[2 * j] * (f32x2){v.x, v.y}; a1 += s[2 * j + 1] * (f32x2){v.z, v.w}; }
;                 const float yo = yc[q] + (a0.x + a0.y) + (a1.x + a1.y);
;                 const float mean = wave_sum(yo) * (1.0f / 64.0f); const float d = yo - mean; const float var = wave_sum(d * d) * (1.0f / 64.0f);
;                 const float o = (d * rsqrtf(var + 64e-5f) * gnw + gnb + bc[q]) * gc[q];
;                 YCAT[(size_t)(m0 + bt * 4 + q) * DM + ch] = (bf16_t)(cvt_pk_bf16(o, 0.f) & 0xffffu);
	v_pk_fma_f32 v[88:89], v[4:5], v[88:89], v[108:109]
	v_pk_fma_f32 v[90:91], v[2:3], v[90:91], v[110:111]
	v_mov_b32_e32 v107, v88
	v_mov_b32_e32 v106, v90
	v_mov_b32_e32 v88, v91
	v_pk_add_f32 v[88:89], v[106:107], v[88:89]
	v_add_f32_e32 v85, v105, v89
	v_add_f32_e32 v85, v88, v85
	s_nop 1
	v_add_f32_dpp v87, v85, v85 quad_perm:[1,0,3,2] row_mask:0xf bank_mask:0xf bound_ctrl:1
	s_nop 1
	v_add_f32_dpp v87, v87, v87 quad_perm:[2,3,0,1] row_mask:0xf bank_mask:0xf bound_ctrl:1
	s_nop 1
	v_add_f32_dpp v87, v87, v87 row_ror:4 row_mask:0xf bank_mask:0xf bound_ctrl:1
	s_nop 1
	v_add_f32_dpp v87, v87, v87 row_ror:8 row_mask:0xf bank_mask:0xf bound_ctrl:1
	s_nop 0
	v_readlane_b32 s7, v87, 16
	v_readlane_b32 s16, v87, 48
	v_readlane_b32 s14, v87, 0
	v_readlane_b32 s15, v87, 32
	v_mov_b32_e32 v88, s7
	v_mov_b32_e32 v89, s16
	v_pk_add_f32 v[88:89], s[14:15], v[88:89]
	s_nop 0
	v_add_f32_e32 v87, v88, v89
	v_fmac_f32_e32 v85, 0xbc800000, v87
	v_mul_f32_e32 v87, v85, v85
	s_nop 1
	v_mov_b32_dpp v87, v87 quad_perm:[1,0,3,2] row_mask:0xf bank_mask:0xf bound_ctrl:1
	v_fmac_f32_e32 v87, v85, v85
	s_nop 1
	v_add_f32_dpp v87, v87, v87 quad_perm:[2,3,0,1] row_mask:0xf bank_mask:0xf bound_ctrl:1
	s_nop 1
	v_add_f32_dpp v87, v87, v87 row_ror:4 row_mask:0xf bank_mask:0xf bound_ctrl:1
	s_nop 1
	v_add_f32_dpp v87, v87, v87 row_ror:8 row_mask:0xf bank_mask:0xf bound_ctrl:1
	s_nop 0
	v_readlane_b32 s7, v87, 16
	v_readlane_b32 s16, v87, 48
	v_readlane_b32 s14, v87, 0
	v_readlane_b32 s15, v87, 32
	v_mov_b32_e32 v88, s7
	v_mov_b32_e32 v89, s16
	v_pk_add_f32 v[88:89], s[14:15], v[88:89]
	s_mov_b64 s[14:15], 0x4000
	v_add_f32_e32 v87, v88, v89
	v_fmamk_f32 v87, v87, 0x3c800000, v185
	v_cmp_gt_f32_e32 vcc, s3, v87
	v_mul_f32_e32 v88, 0x4b800000, v87
	v_lshl_add_u64 v[76:77], v[76:77], 0, s[14:15]
	v_cndmask_b32_e32 v87, v87, v88, vcc
	v_rsq_f32_e32 v87, v87
	s_mov_b64 s[14:15], 0x4800
	v_lshl_add_u64 v[78:79], v[78:79], 0, s[14:15]
	s_mov_b64 s[14:15], 0x3000
	v_mul_f32_e32 v88, 0x45800000, v87
	v_cndmask_b32_e32 v87, v87, v88, vcc
	v_mul_f32_e32 v85, v85, v87
	v_fma_f32 v85, v95, v85, v96
	v_add_f32_e32 v84, v84, v85
	v_mul_f32_e32 v84, v86, v84
	v_cvt_pk_bf16_f32 v86, v84, v137
	v_add_co_u32_e32 v84, vcc, 0x16203000, v92
	v_lshl_add_u64 v[80:81], v[80:81], 0, s[14:15]
	s_nop 0
	v_addc_co_u32_e32 v85, vcc, 0, v93, vcc
	global_store_short v[84:85], v86, off
	s_waitcnt lgkmcnt(0)
	s_waitcnt vmcnt(0)
	v_lshlrev_b32_e32 v70, 16, v144
	v_lshlrev_b32_e32 v71, 16, v145
	v_lshlrev_b32_e32 v72, 16, v146
	v_lshlrev_b32_e32 v73, 16, v147
	v_lshlrev_b32_e32 v67, 16, v149
	v_lshlrev_b32_e32 v66, 16, v148
	v_lshlrev_b32_e32 v69, 16, v151
	v_lshlrev_b32_e32 v68, 16, v150
	v_mov_b64_e32 v[90:91], v[72:73]
	v_mov_b64_e32 v[84:85], v[66:67]
	v_mov_b64_e32 v[88:89], v[70:71]
	v_mov_b64_e32 v[86:87], v[68:69]
	s_cbranch_scc0 .LBB0_92
	ds_write2st64_b32 v94, v101, v102 offset1:1
	ds_write2st64_b32 v94, v103, v104 offset0:2 offset1:3
	s_waitcnt lgkmcnt(0)
	v_mov_b32_e32 v76, s11
	ds_read_b128 v[78:81], v76
	ds_read_b128 v[82:85], v76 offset:16
	ds_read_b128 v[86:89], v76 offset:32
	ds_read_b128 v[90:93], v76 offset:48
	v_readlane_b32 s6, v251, 12
	s_waitcnt lgkmcnt(3)
	v_pk_fma_f32 v[78:79], v[42:43], v[78:79], 0 op_sel_hi:[1,1,0]
	v_pk_fma_f32 v[80:81], v[44:45], v[80:81], 0 op_sel_hi:[1,1,0]
	s_waitcnt lgkmcnt(2)
	v_pk_fma_f32 v[78:79], v[48:49], v[82:83], v[78:79]
	v_pk_fma_f32 v[80:81], v[50:51], v[84:85], v[80:81]
	s_waitcnt lgkmcnt(1)
	v_pk_fma_f32 v[78:79], v[54:55], v[86:87], v[78:79]
	v_pk_fma_f32 v[80:81], v[58:59], v[88:89], v[80:81]
	s_waitcnt lgkmcnt(0)
	v_pk_fma_f32 v[82:83], v[60:61], v[90:91], v[78:79]
	v_pk_fma_f32 v[84:85], v[62:63], v[92:93], v[80:81]
	ds_read_b128 v[78:81], v76 offset:64
	v_readlane_b32 s7, v251, 13
	s_add_i32 s10, s10, s46
	s_waitcnt lgkmcnt(0)
	v_pk_fma_f32 v[82:83], v[56:57], v[78:79], v[82:83]
	v_pk_fma_f32 v[84:85], v[64:65], v[80:81], v[84:85]
	ds_read_b128 v[78:81], v76 offset:80
	v_lshl_add_u64 v[74:75], v[74:75], 1, s[6:7]
	s_or_b32 s6, s13, 28
	s_waitcnt lgkmcnt(0)
	v_pk_fma_f32 v[82:83], v[46:47], v[78:79], v[82:83]
	v_pk_fma_f32 v[84:85], v[52:53], v[80:81], v[84:85]
	ds_read_b128 v[78:81], v76 offset:96
	s_waitcnt lgkmcnt(0)
	v_pk_fma_f32 v[82:83], v[38:39], v[78:79], v[82:83]
	v_pk_fma_f32 v[84:85], v[40:41], v[80:81], v[84:85]
	ds_read_b128 v[78:81], v76 offset:112
	s_waitcnt lgkmcnt(0)
	v_pk_fma_f32 v[82:83], v[28:29], v[78:79], v[82:83]
	v_pk_fma_f32 v[84:85], v[30:31], v[80:81], v[84:85]
	ds_read_b128 v[78:81], v76 offset:128
	s_waitcnt lgkmcnt(0)
	v_pk_fma_f32 v[82:83], v[34:35], v[78:79], v[82:83]
	v_pk_fma_f32 v[84:85], v[36:37], v[80:81], v[84:85]
	ds_read_b128 v[78:81], v76 offset:144
	s_waitcnt lgkmcnt(0)
	v_pk_fma_f32 v[82:83], v[26:27], v[78:79], v[82:83]
	v_pk_fma_f32 v[84:85], v[32:33], v[80:81], v[84:85]
	ds_read_b128 v[78:81], v76 offset:160
	s_waitcnt lgkmcnt(0)
	v_pk_fma_f32 v[82:83], v[20:21], v[78:79], v[82:83]
	v_pk_fma_f32 v[84:85], v[24:25], v[80:81], v[84:85]
	ds_read_b128 v[78:81], v76 offset:176
	s_waitcnt lgkmcnt(0)
	v_pk_fma_f32 v[82:83], v[14:15], v[78:79], v[82:83]
	v_pk_fma_f32 v[84:85], v[16:17], v[80:81], v[84:85]
	ds_read_b128 v[78:81], v76 offset:192
	s_waitcnt lgkmcnt(0)
	v_pk_fma_f32 v[82:83], v[18:19], v[78:79], v[82:83]
	v_pk_fma_f32 v[84:85], v[22:23], v[80:81], v[84:85]
	ds_read_b128 v[78:81], v76 offset:208
	s_waitcnt lgkmcnt(0)
	v_pk_fma_f32 v[82:83], v[10:11], v[78:79], v[82:83]
	v_pk_fma_f32 v[84:85], v[12:13], v[80:81], v[84:85]
	ds_read_b128 v[78:81], v76 offset:224
	s_waitcnt lgkmcnt(0)
	v_pk_fma_f32 v[82:83], v[6:7], v[78:79], v[82:83]
	v_pk_fma_f32 v[84:85], v[8:9], v[80:81], v[84:85]
	ds_read_b128 v[78:81], v76 offset:240
	s_waitcnt lgkmcnt(0)
; __device__ __forceinline__ unsigned cvt_pk_bf16(float lo, float hi) { unsigned r; asm volatile("v_cvt_pk_bf16_f32 %0, %1, %2" : "=v"(r) : "v"(lo), "v"(hi)); return r; }
; #define LAS __attribute__((address_space(3)))
; __device__ __forceinline__ void rwkv_out(const Params& p, int l, int wave, int lane, LAS unsigned char* lds) {
;     ...
;             for (int q = 0; q < 4; ++q) {
;                 const LAS f32x4* Q4 = (const LAS f32x4*)(qb + q * 64);
;                 f32x2 a0 = {0.f, 0.f}, a1 = {0.f, 0.f};
; #pragma unroll
;                 for (int j = 0; j < 16; ++j) { const f32x4 v = Q4[j]; a0 += s[2 * j] * (f32x2){v.x, v.y}; a1 += s[2 * j + 1] * (f32x2){v.z, v.w}; }
;                 const float yo = yc[q] + (a0.x + a0.y) + (a1.x + a1.y);
;                 const float mean = wave_sum(yo) * (1.0f / 64.0f); const float d = yo - mean; const float var = wave_sum(d * d) * (1.0f / 64.0f);
;                 const float o = (d * rsqrtf(var + 64e-5f) * gnw + gnb + bc[q]) * gc[q];
;                 YCAT[(size_t)(m0 + bt * 4 + q) * DM + ch] = (bf16_t)(cvt_pk_bf16(o, 0.f) & 0xffffu);
	v_pk_fma_f32 v[78:79], v[4:5], v[78:79], v[82:83]
	v_pk_fma_f32 v[80:81], v[2:3], v[80:81], v[84:85]
	v_mov_b32_e32 v83, v78
	v_mov_b32_e32 v82, v80
	v_mov_b32_e32 v78, v81
	v_pk_add_f32 v[78:79], v[82:83], v[78:79]
	s_nop 0
	v_add_f32_e32 v77, v100, v79
	v_add_f32_e32 v77, v78, v77
	s_nop 1
	v_add_f32_dpp v78, v77, v77 quad_perm:[1,0,3,2] row_mask:0xf bank_mask:0xf bound_ctrl:1
	s_nop 1
	v_add_f32_dpp v78, v78, v78 quad_perm:[2,3,0,1] row_mask:0xf bank_mask:0xf bound_ctrl:1
	s_nop 1
	v_add_f32_dpp v78, v78, v78 row_ror:4 row_mask:0xf bank_mask:0xf bound_ctrl:1
	s_nop 1
	v_add_f32_dpp v78, v78, v78 row_ror:8 row_mask:0xf bank_mask:0xf bound_ctrl:1
	s_nop 0
	v_readlane_b32 s7, v78, 16
	v_readlane_b32 s16, v78, 48
	v_readlane_b32 s14, v78, 0
	v_readlane_b32 s15, v78, 32
	v_mov_b32_e32 v78, s7
	v_mov_b32_e32 v79, s16
	v_pk_add_f32 v[78:79], s[14:15], v[78:79]
	s_nop 0
	v_add_f32_e32 v78, v78, v79
	v_fmac_f32_e32 v77, 0xbc800000, v78
	v_mul_f32_e32 v78, v77, v77
	s_nop 1
	v_mov_b32_dpp v78, v78 quad_perm:[1,0,3,2] row_mask:0xf bank_mask:0xf bound_ctrl:1
	v_fmac_f32_e32 v78, v77, v77
	s_nop 1
	v_add_f32_dpp v78, v78, v78 quad_perm:[2,3,0,1] row_mask:0xf bank_mask:0xf bound_ctrl:1
	s_nop 1
	v_add_f32_dpp v78, v78, v78 row_ror:4 row_mask:0xf bank_mask:0xf bound_ctrl:1
	s_nop 1
	v_add_f32_dpp v78, v78, v78 row_ror:8 row_mask:0xf bank_mask:0xf bound_ctrl:1
	s_nop 0
	v_readlane_b32 s7, v78, 16
	v_readlane_b32 s16, v78, 48
	v_readlane_b32 s14, v78, 0
	v_readlane_b32 s15, v78, 32
	v_mov_b32_e32 v78, s7
	v_mov_b32_e32 v79, s16
	v_pk_add_f32 v[78:79], s[14:15], v[78:79]
	s_ashr_i32 s7, s6, 31
	v_add_f32_e32 v78, v78, v79
	v_fmamk_f32 v78, v78, 0x3c800000, v185
	v_cmp_gt_f32_e32 vcc, s3, v78
	v_mul_f32_e32 v79, 0x4b800000, v78
	s_lshl_b64 s[6:7], s[6:7], 12
	v_cndmask_b32_e32 v78, v78, v79, vcc
	v_rsq_f32_e32 v78, v78
	s_nop 0
	v_mul_f32_e32 v79, 0x45800000, v78
	v_cndmask_b32_e32 v78, v78, v79, vcc
	v_mul_f32_e32 v77, v77, v78
	v_fma_f32 v77, v95, v77, v96
	v_add_f32_e32 v71, v77, v71
	v_mul_f32_e32 v71, v71, v73
	v_lshl_add_u64 v[78:79], v[74:75], 0, s[6:7]
	v_cvt_pk_bf16_f32 v71, v71, v137
	global_store_short v[78:79], v71, off
	ds_read_b128 v[78:81], v76 offset:256
	ds_read_b128 v[82:85], v76 offset:272
	ds_read_b128 v[86:89], v76 offset:288
	ds_read_b128 v[90:93], v76 offset:304
	s_waitcnt lgkmcnt(3)
	v_pk_fma_f32 v[78:79], v[42:43], v[78:79], 0 op_sel_hi:[1,1,0]
	v_pk_fma_f32 v[80:81], v[44:45], v[80:81], 0 op_sel_hi:[1,1,0]
	s_waitcnt lgkmcnt(2)
	v_pk_fma_f32 v[78:79], v[48:49], v[82:83], v[78:79]
	v_pk_fma_f32 v[80:81], v[50:51], v[84:85], v[80:81]
	s_waitcnt lgkmcnt(1)
	v_pk_fma_f32 v[78:79], v[54:55], v[86:87], v[78:79]
	v_pk_fma_f32 v[80:81], v[58:59], v[88:89], v[80:81]
	s_waitcnt lgkmcnt(0)
	v_pk_fma_f32 v[82:83], v[60:61], v[90:91], v[78:79]
	v_pk_fma_f32 v[84:85], v[62:63], v[92:93], v[80:81]
	ds_read_b128 v[78:81], v76 offset:320
	s_waitcnt lgkmcnt(0)
	v_pk_fma_f32 v[82:83], v[56:57], v[78:79], v[82:83]
	v_pk_fma_f32 v[84:85], v[64:65], v[80:81], v[84:85]
	ds_read_b128 v[78:81], v76 offset:336
	s_waitcnt lgkmcnt(0)
	v_pk_fma_f32 v[82:83], v[46:47], v[78:79], v[82:83]
	v_pk_fma_f32 v[84:85], v[52:53], v[80:81], v[84:85]
	ds_read_b128 v[78:81], v76 offset:352
	s_waitcnt lgkmcnt(0)
	v_pk_fma_f32 v[82:83], v[38:39], v[78:79], v[82:83]
	v_pk_fma_f32 v[84:85], v[40:41], v[80:81], v[84:85]
	ds_read_b128 v[78:81], v76 offset:368
	s_waitcnt lgkmcnt(0)
	v_pk_fma_f32 v[82:83], v[28:29], v[78:79], v[82:83]
	v_pk_fma_f32 v[84:85], v[30:31], v[80:81], v[84:85]
	ds_read_b128 v[78:81], v76 offset:384
	s_waitcnt lgkmcnt(0)
	v_pk_fma_f32 v[82:83], v[34:35], v[78:79], v[82:83]
	v_pk_fma_f32 v[84:85], v[36:37], v[80:81], v[84:85]
	ds_read_b128 v[78:81], v76 offset:400
	s_waitcnt lgkmcnt(0)
	v_pk_fma_f32 v[82:83], v[26:27], v[78:79], v[82:83]
	v_pk_fma_f32 v[84:85], v[32:33], v[80:81], v[84:85]
	ds_read_b128 v[78:81], v76 offset:416
	s_waitcnt lgkmcnt(0)
	v_pk_fma_f32 v[82:83], v[20:21], v[78:79], v[82:83]
	v_pk_fma_f32 v[84:85], v[24:25], v[80:81], v[84:85]
	ds_read_b128 v[78:81], v76 offset:432
	s_waitcnt lgkmcnt(0)
	v_pk_fma_f32 v[82:83], v[14:15], v[78:79], v[82:83]
	v_pk_fma_f32 v[84:85], v[16:17], v[80:81], v[84:85]
	ds_read_b128 v[78:81], v76 offset:448
	s_waitcnt lgkmcnt(0)
	v_pk_fma_f32 v[82:83], v[18:19], v[78:79], v[82:83]
	v_pk_fma_f32 v[84:85], v[22:23], v[80:81], v[84:85]
	ds_read_b128 v[78:81], v76 offset:464
	s_waitcnt lgkmcnt(0)
	v_pk_fma_f32 v[82:83], v[10:11], v[78:79], v[82:83]
	v_pk_fma_f32 v[84:85], v[12:13], v[80:81], v[84:85]
	ds_read_b128 v[78:81], v76 offset:480
	s_waitcnt lgkmcnt(0)
	v_pk_fma_f32 v[82:83], v[6:7], v[78:79], v[82:83]
	v_pk_fma_f32 v[84:85], v[8:9], v[80:81], v[84:85]
	ds_read_b128 v[78:81], v76 offset:496
	s_waitcnt lgkmcnt(0)
; __device__ __forceinline__ unsigned cvt_pk_bf16(float lo, float hi) { unsigned r; asm volatile("v_cvt_pk_bf16_f32 %0, %1, %2" : "=v"(r) : "v"(lo), "v"(hi)); return r; }
; #define LAS __attribute__((address_space(3)))
; __device__ __forceinline__ void rwkv_out(const Params& p, int l, int wave, int lane, LAS unsigned char* lds) {
;     ...
;             for (int q = 0; q < 4; ++q) {
;                 const LAS f32x4* Q4 = (const LAS f32x4*)(qb + q * 64);
;                 f32x2 a0 = {0.f, 0.f}, a1 = {0.f, 0.f};
; #pragma unroll
;                 for (int j = 0; j < 16; ++j) { const f32x4 v = Q4[j]; a0 += s[2 * j] * (f32x2){v.x, v.y}; a1 += s[2 * j + 1] * (f32x2){v.z, v.w}; }
;                 const float yo = yc[q] + (a0.x + a0.y) + (a1.x + a1.y);
;                 const float mean = wave_sum(yo) * (1.0f / 64.0f); const float d = yo - mean; const float var = wave_sum(d * d) * (1.0f / 64.0f);
;                 const float o = (d * rsqrtf(var + 64e-5f) * gnw + gnb + bc[q]) * gc[q];
;                 YCAT[(size_t)(m0 + bt * 4 + q) * DM + ch] = (bf16_t)(cvt_pk_bf16(o, 0.f) & 0xffffu);
	v_pk_fma_f32 v[78:79], v[4:5], v[78:79], v[82:83]
	v_pk_fma_f32 v[80:81], v[2:3], v[80:81], v[84:85]
	v_mov_b32_e32 v83, v78
	v_mov_b32_e32 v82, v80
	v_mov_b32_e32 v78, v81
	v_pk_add_f32 v[78:79], v[82:83], v[78:79]
	s_nop 0
	v_add_f32_e32 v71, v99, v79
	v_add_f32_e32 v71, v78, v71
	s_nop 1
	v_add_f32_dpp v73, v71, v71 quad_perm:[1,0,3,2] row_mask:0xf bank_mask:0xf bound_ctrl:1
	s_nop 1
	v_add_f32_dpp v73, v73, v73 quad_perm:[2,3,0,1] row_mask:0xf bank_mask:0xf bound_ctrl:1
	s_nop 1
	v_add_f32_dpp v73, v73, v73 row_ror:4 row_mask:0xf bank_mask:0xf bound_ctrl:1
	s_nop 1
	v_add_f32_dpp v73, v73, v73 row_ror:8 row_mask:0xf bank_mask:0xf bound_ctrl:1
	s_nop 0
	v_readlane_b32 s14, v73, 16
	v_readlane_b32 s15, v73, 48
	v_readlane_b32 s6, v73, 0
	v_readlane_b32 s7, v73, 32
	v_mov_b32_e32 v78, s14
	v_mov_b32_e32 v79, s15
	v_pk_add_f32 v[78:79], s[6:7], v[78:79]
	s_nop 0
	v_add_f32_e32 v73, v78, v79
	v_fmac_f32_e32 v71, 0xbc800000, v73
	v_mul_f32_e32 v73, v71, v71
	s_nop 1
	v_mov_b32_dpp v73, v73 quad_perm:[1,0,3,2] row_mask:0xf bank_mask:0xf bound_ctrl:1
	v_fmac_f32_e32 v73, v71, v71
	s_nop 1
	v_add_f32_dpp v73, v73, v73 quad_perm:[2,3,0,1] row_mask:0xf bank_mask:0xf bound_ctrl:1
	s_nop 1
	v_add_f32_dpp v73, v73, v73 row_ror:4 row_mask:0xf bank_mask:0xf bound_ctrl:1
	s_nop 1
	v_add_f32_dpp v73, v73, v73 row_ror:8 row_mask:0xf bank_mask:0xf bound_ctrl:1
	s_nop 0
	v_readlane_b32 s14, v73, 16
	v_readlane_b32 s15, v73, 48
	v_readlane_b32 s6, v73, 0
	v_readlane_b32 s7, v73, 32
	v_mov_b32_e32 v78, s14
	v_mov_b32_e32 v79, s15
	v_pk_add_f32 v[78:79], s[6:7], v[78:79]
	s_or_b32 s6, s13, 29
	v_add_f32_e32 v73, v78, v79
	v_fmamk_f32 v73, v73, 0x3c800000, v185
	v_cmp_gt_f32_e32 vcc, s3, v73
	v_mul_f32_e32 v77, 0x4b800000, v73
	s_ashr_i32 s7, s6, 31
	v_cndmask_b32_e32 v73, v73, v77, vcc
	v_rsq_f32_e32 v73, v73
	s_lshl_b64 s[6:7], s[6:7], 12
	v_mul_f32_e32 v77, 0x45800000, v73
	v_cndmask_b32_e32 v73, v73, v77, vcc
	v_mul_f32_e32 v71, v71, v73
	v_fma_f32 v71, v95, v71, v96
	v_add_f32_e32 v70, v71, v70
	v_mul_f32_e32 v70, v70, v72
	v_cvt_pk_bf16_f32 v72, v70, v137
	v_lshl_add_u64 v[70:71], v[74:75], 0, s[6:7]
	global_store_short v[70:71], v72, off
	ds_read_b128 v[70:73], v76 offset:512
	ds_read_b128 v[78:81], v76 offset:528
	ds_read_b128 v[82:85], v76 offset:544
	ds_read_b128 v[86:89], v76 offset:560
	s_waitcnt lgkmcnt(3)
	v_pk_fma_f32 v[70:71], v[42:43], v[70:71], 0 op_sel_hi:[1,1,0]
	v_pk_fma_f32 v[72:73], v[44:45], v[72:73], 0 op_sel_hi:[1,1,0]
	s_waitcnt lgkmcnt(2)
	v_pk_fma_f32 v[70:71], v[48:49], v[78:79], v[70:71]
	v_pk_fma_f32 v[72:73], v[50:51], v[80:81], v[72:73]
	s_waitcnt lgkmcnt(1)
	v_pk_fma_f32 v[70:71], v[54:55], v[82:83], v[70:71]
	v_pk_fma_f32 v[72:73], v[58:59], v[84:85], v[72:73]
	s_waitcnt lgkmcnt(0)
	v_pk_fma_f32 v[78:79], v[60:61], v[86:87], v[70:71]
	v_pk_fma_f32 v[80:81], v[62:63], v[88:89], v[72:73]
	ds_read_b128 v[70:73], v76 offset:576
	s_waitcnt lgkmcnt(0)
	v_pk_fma_f32 v[78:79], v[56:57], v[70:71], v[78:79]
	v_pk_fma_f32 v[80:81], v[64:65], v[72:73], v[80:81]
	ds_read_b128 v[70:73], v76 offset:592
	s_waitcnt lgkmcnt(0)
	v_pk_fma_f32 v[78:79], v[46:47], v[70:71], v[78:79]
	v_pk_fma_f32 v[80:81], v[52:53], v[72:73], v[80:81]
	ds_read_b128 v[70:73], v76 offset:608
	s_waitcnt lgkmcnt(0)
	v_pk_fma_f32 v[78:79], v[38:39], v[70:71], v[78:79]
	v_pk_fma_f32 v[80:81], v[40:41], v[72:73], v[80:81]
	ds_read_b128 v[70:73], v76 offset:624
	s_waitcnt lgkmcnt(0)
	v_pk_fma_f32 v[78:79], v[28:29], v[70:71], v[78:79]
	v_pk_fma_f32 v[80:81], v[30:31], v[72:73], v[80:81]
	ds_read_b128 v[70:73], v76 offset:640
	s_waitcnt lgkmcnt(0)
	v_pk_fma_f32 v[78:79], v[34:35], v[70:71], v[78:79]
	v_pk_fma_f32 v[80:81], v[36:37], v[72:73], v[80:81]
	ds_read_b128 v[70:73], v76 offset:656
	s_waitcnt lgkmcnt(0)
	v_pk_fma_f32 v[78:79], v[26:27], v[70:71], v[78:79]
	v_pk_fma_f32 v[80:81], v[32:33], v[72:73], v[80:81]
	ds_read_b128 v[70:73], v76 offset:672
	s_waitcnt lgkmcnt(0)
	v_pk_fma_f32 v[78:79], v[20:21], v[70:71], v[78:79]
	v_pk_fma_f32 v[80:81], v[24:25], v[72:73], v[80:81]
	ds_read_b128 v[70:73], v76 offset:688
	s_waitcnt lgkmcnt(0)
	v_pk_fma_f32 v[78:79], v[14:15], v[70:71], v[78:79]
	v_pk_fma_f32 v[80:81], v[16:17], v[72:73], v[80:81]
	ds_read_b128 v[70:73], v76 offset:704
	s_waitcnt lgkmcnt(0)
	v_pk_fma_f32 v[78:79], v[18:19], v[70:71], v[78:79]
	v_pk_fma_f32 v[80:81], v[22:23], v[72:73], v[80:81]
	ds_read_b128 v[70:73], v76 offset:720
	s_waitcnt lgkmcnt(0)
	v_pk_fma_f32 v[78:79], v[10:11], v[70:71], v[78:79]
	v_pk_fma_f32 v[80:81], v[12:13], v[72:73], v[80:81]
	ds_read_b128 v[70:73], v76 offset:736
	s_waitcnt lgkmcnt(0)
	v_pk_fma_f32 v[78:79], v[6:7], v[70:71], v[78:79]
	v_pk_fma_f32 v[80:81], v[8:9], v[72:73], v[80:81]
	ds_read_b128 v[70:73], v76 offset:752
	s_waitcnt lgkmcnt(0)
; __device__ __forceinline__ unsigned cvt_pk_bf16(float lo, float hi) { unsigned r; asm volatile("v_cvt_pk_bf16_f32 %0, %1, %2" : "=v"(r) : "v"(lo), "v"(hi)); return r; }
; #define LAS __attribute__((address_space(3)))
; #define WAVE_SYNC() asm volatile("s_waitcnt lgkmcnt(0)" ::: "memory")
; __device__ __forceinline__ void rwkv_out(const Params& p, int l, int wave, int lane, LAS unsigned char* lds) {
;     ...
;             for (int q = 0; q < 4; ++q) {
;                 const LAS f32x4* Q4 = (const LAS f32x4*)(qb + q * 64);
;                 f32x2 a0 = {0.f, 0.f}, a1 = {0.f, 0.f};
; #pragma unroll
;                 for (int j = 0; j < 16; ++j) { const f32x4 v = Q4[j]; a0 += s[2 * j] * (f32x2){v.x, v.y}; a1 += s[2 * j + 1] * (f32x2){v.z, v.w}; }
;                 const float yo = yc[q] + (a0.x + a0.y) + (a1.x + a1.y);
;                 const float mean = wave_sum(yo) * (1.0f / 64.0f); const float d = yo - mean; const float var = wave_sum(d * d) * (1.0f / 64.0f);
;                 const float o = (d * rsqrtf(var + 64e-5f) * gnw + gnb + bc[q]) * gc[q];
;                 YCAT[(size_t)(m0 + bt * 4 + q) * DM + ch] = (bf16_t)(cvt_pk_bf16(o, 0.f) & 0xffffu);
;             }
;             WAVE_SYNC();
;         }
;     }
	v_pk_fma_f32 v[70:71], v[4:5], v[70:71], v[78:79]
	v_pk_fma_f32 v[72:73], v[2:3], v[72:73], v[80:81]
	v_mov_b32_e32 v79, v70
	v_mov_b32_e32 v78, v72
	v_mov_b32_e32 v70, v73
	v_pk_add_f32 v[70:71], v[78:79], v[70:71]
	s_nop 0
	v_add_f32_e32 v71, v98, v71
	v_add_f32_e32 v72, v70, v71
	s_nop 1
	v_add_f32_dpp v70, v72, v72 quad_perm:[1,0,3,2] row_mask:0xf bank_mask:0xf bound_ctrl:1
	s_nop 1
	v_add_f32_dpp v70, v70, v70 quad_perm:[2,3,0,1] row_mask:0xf bank_mask:0xf bound_ctrl:1
	s_nop 1
	v_add_f32_dpp v70, v70, v70 row_ror:4 row_mask:0xf bank_mask:0xf bound_ctrl:1
	s_nop 1
	v_add_f32_dpp v70, v70, v70 row_ror:8 row_mask:0xf bank_mask:0xf bound_ctrl:1
	s_nop 0
	v_readlane_b32 s14, v70, 16
	v_readlane_b32 s15, v70, 48
	v_readlane_b32 s6, v70, 0
	v_readlane_b32 s7, v70, 32
	v_mov_b32_e32 v70, s14
	v_mov_b32_e32 v71, s15
	v_pk_add_f32 v[70:71], s[6:7], v[70:71]
	s_nop 0
	v_add_f32_e32 v70, v70, v71
	v_fmac_f32_e32 v72, 0xbc800000, v70
	v_mul_f32_e32 v70, v72, v72
	s_nop 1
	v_mov_b32_dpp v70, v70 quad_perm:[1,0,3,2] row_mask:0xf bank_mask:0xf bound_ctrl:1
	v_fmac_f32_e32 v70, v72, v72
	s_nop 1
	v_add_f32_dpp v70, v70, v70 quad_perm:[2,3,0,1] row_mask:0xf bank_mask:0xf bound_ctrl:1
	s_nop 1
	v_add_f32_dpp v70, v70, v70 row_ror:4 row_mask:0xf bank_mask:0xf bound_ctrl:1
	s_nop 1
	v_add_f32_dpp v70, v70, v70 row_ror:8 row_mask:0xf bank_mask:0xf bound_ctrl:1
	s_nop 0
	v_readlane_b32 s14, v70, 16
	v_readlane_b32 s15, v70, 48
	v_readlane_b32 s6, v70, 0
	v_readlane_b32 s7, v70, 32
	v_mov_b32_e32 v70, s14
	v_mov_b32_e32 v71, s15
	v_pk_add_f32 v[70:71], s[6:7], v[70:71]
	s_or_b32 s6, s13, 30
	v_add_f32_e32 v70, v70, v71
	v_fmamk_f32 v70, v70, 0x3c800000, v185
	v_cmp_gt_f32_e32 vcc, s3, v70
	v_mul_f32_e32 v71, 0x4b800000, v70
	s_ashr_i32 s7, s6, 31
	v_cndmask_b32_e32 v70, v70, v71, vcc
	v_rsq_f32_e32 v70, v70
	s_lshl_b64 s[6:7], s[6:7], 12
	v_mul_f32_e32 v71, 0x45800000, v70
	v_cndmask_b32_e32 v70, v70, v71, vcc
	v_mul_f32_e32 v70, v72, v70
	v_fma_f32 v70, v95, v70, v96
	v_add_f32_e32 v67, v70, v67
	v_mul_f32_e32 v67, v67, v69
	v_lshl_add_u64 v[70:71], v[74:75], 0, s[6:7]
	v_cvt_pk_bf16_f32 v67, v67, v137
	global_store_short v[70:71], v67, off
	ds_read_b128 v[70:73], v76 offset:768
	ds_read_b128 v[78:81], v76 offset:784
	ds_read_b128 v[82:85], v76 offset:800
	ds_read_b128 v[86:89], v76 offset:816
	s_waitcnt lgkmcnt(3)
	v_pk_fma_f32 v[42:43], v[42:43], v[70:71], 0 op_sel_hi:[1,1,0]
	v_pk_fma_f32 v[44:45], v[44:45], v[72:73], 0 op_sel_hi:[1,1,0]
	s_waitcnt lgkmcnt(2)
	v_pk_fma_f32 v[42:43], v[48:49], v[78:79], v[42:43]
	v_pk_fma_f32 v[44:45], v[50:51], v[80:81], v[44:45]
	s_waitcnt lgkmcnt(1)
	v_pk_fma_f32 v[42:43], v[54:55], v[82:83], v[42:43]
	v_pk_fma_f32 v[44:45], v[58:59], v[84:85], v[44:45]
	s_waitcnt lgkmcnt(0)
	v_pk_fma_f32 v[48:49], v[60:61], v[86:87], v[42:43]
	v_pk_fma_f32 v[50:51], v[62:63], v[88:89], v[44:45]
	ds_read_b128 v[42:45], v76 offset:832
	s_waitcnt lgkmcnt(0)
	v_pk_fma_f32 v[48:49], v[56:57], v[42:43], v[48:49]
	v_pk_fma_f32 v[50:51], v[64:65], v[44:45], v[50:51]
	ds_read_b128 v[42:45], v76 offset:848
	s_waitcnt lgkmcnt(0)
	v_pk_fma_f32 v[46:47], v[46:47], v[42:43], v[48:49]
	v_pk_fma_f32 v[48:49], v[52:53], v[44:45], v[50:51]
	ds_read_b128 v[42:45], v76 offset:864
	s_waitcnt lgkmcnt(0)
	v_pk_fma_f32 v[42:43], v[38:39], v[42:43], v[46:47]
	v_pk_fma_f32 v[44:45], v[40:41], v[44:45], v[48:49]
	ds_read_b128 v[38:41], v76 offset:880
	s_waitcnt lgkmcnt(0)
	v_pk_fma_f32 v[38:39], v[28:29], v[38:39], v[42:43]
	v_pk_fma_f32 v[40:41], v[30:31], v[40:41], v[44:45]
	ds_read_b128 v[28:31], v76 offset:896
	s_waitcnt lgkmcnt(0)
	v_pk_fma_f32 v[34:35], v[34:35], v[28:29], v[38:39]
	v_pk_fma_f32 v[36:37], v[36:37], v[30:31], v[40:41]
	ds_read_b128 v[28:31], v76 offset:912
	s_waitcnt lgkmcnt(0)
	v_pk_fma_f32 v[34:35], v[26:27], v[28:29], v[34:35]
	ds_read_b128 v[26:29], v76 offset:928
	v_pk_fma_f32 v[30:31], v[32:33], v[30:31], v[36:37]
	s_waitcnt lgkmcnt(0)
	v_pk_fma_f32 v[20:21], v[20:21], v[26:27], v[34:35]
	v_pk_fma_f32 v[28:29], v[24:25], v[28:29], v[30:31]
	ds_read_b128 v[24:27], v76 offset:944
	s_waitcnt lgkmcnt(0)
	v_pk_fma_f32 v[20:21], v[14:15], v[24:25], v[20:21]
	v_pk_fma_f32 v[24:25], v[16:17], v[26:27], v[28:29]
	ds_read_b128 v[14:17], v76 offset:960
	s_waitcnt lgkmcnt(0)
	v_pk_fma_f32 v[18:19], v[18:19], v[14:15], v[20:21]
	v_pk_fma_f32 v[20:21], v[22:23], v[16:17], v[24:25]
	ds_read_b128 v[14:17], v76 offset:976
	s_waitcnt lgkmcnt(0)
	v_pk_fma_f32 v[14:15], v[10:11], v[14:15], v[18:19]
	v_pk_fma_f32 v[16:17], v[12:13], v[16:17], v[20:21]
	ds_read_b128 v[10:13], v76 offset:992
	s_waitcnt lgkmcnt(0)
	v_pk_fma_f32 v[10:11], v[6:7], v[10:11], v[14:15]
	v_pk_fma_f32 v[12:13], v[8:9], v[12:13], v[16:17]
	ds_read_b128 v[6:9], v76 offset:1008
	s_waitcnt lgkmcnt(0)
	v_pk_fma_f32 v[4:5], v[4:5], v[6:7], v[10:11]
	v_pk_fma_f32 v[2:3], v[2:3], v[8:9], v[12:13]
	v_mov_b32_e32 v7, v4
	v_mov_b32_e32 v6, v2
	v_mov_b32_e32 v4, v3
	v_pk_add_f32 v[2:3], v[6:7], v[4:5]
	s_nop 0
	v_add_f32_e32 v3, v97, v3
	v_add_f32_e32 v4, v2, v3
	s_nop 1
	v_add_f32_dpp v2, v4, v4 quad_perm:[1,0,3,2] row_mask:0xf bank_mask:0xf bound_ctrl:1
	s_nop 1
	v_add_f32_dpp v2, v2, v2 quad_perm:[2,3,0,1] row_mask:0xf bank_mask:0xf bound_ctrl:1
	s_nop 1
	v_add_f32_dpp v2, v2, v2 row_ror:4 row_mask:0xf bank_mask:0xf bound_ctrl:1
	s_nop 1
	v_add_f32_dpp v2, v2, v2 row_ror:8 row_mask:0xf bank_mask:0xf bound_ctrl:1
	s_nop 0
	v_readlane_b32 s14, v2, 16
	v_readlane_b32 s15, v2, 48
	v_readlane_b32 s6, v2, 0
	v_readlane_b32 s7, v2, 32
	v_mov_b32_e32 v2, s14
	v_mov_b32_e32 v3, s15
	v_pk_add_f32 v[2:3], s[6:7], v[2:3]
	s_nop 0
	v_add_f32_e32 v2, v2, v3
	v_fmac_f32_e32 v4, 0xbc800000, v2
	v_mul_f32_e32 v2, v4, v4
	s_nop 1
	v_mov_b32_dpp v2, v2 quad_perm:[1,0,3,2] row_mask:0xf bank_mask:0xf bound_ctrl:1
	v_fmac_f32_e32 v2, v4, v4
	s_nop 1
	v_add_f32_dpp v2, v2, v2 quad_perm:[2,3,0,1] row_mask:0xf bank_mask:0xf bound_ctrl:1
	s_nop 1
	v_add_f32_dpp v2, v2, v2 row_ror:4 row_mask:0xf bank_mask:0xf bound_ctrl:1
	s_nop 1
	v_add_f32_dpp v2, v2, v2 row_ror:8 row_mask:0xf bank_mask:0xf bound_ctrl:1
	s_nop 0
	v_readlane_b32 s14, v2, 16
	v_readlane_b32 s15, v2, 48
	v_readlane_b32 s6, v2, 0
	v_readlane_b32 s7, v2, 32
	v_mov_b32_e32 v2, s14
	v_mov_b32_e32 v3, s15
	v_pk_add_f32 v[2:3], s[6:7], v[2:3]
	s_or_b32 s6, s13, 31
	v_add_f32_e32 v2, v2, v3
	v_fmamk_f32 v2, v2, 0x3c800000, v185
	v_cmp_gt_f32_e32 vcc, s3, v2
	v_mul_f32_e32 v3, 0x4b800000, v2
	s_ashr_i32 s7, s6, 31
	v_cndmask_b32_e32 v2, v2, v3, vcc
	v_rsq_f32_e32 v2, v2
	s_lshl_b64 s[6:7], s[6:7], 12
	v_readlane_b32 s3, v252, 45
	s_add_i32 s12, s12, s3
	v_mul_f32_e32 v3, 0x45800000, v2
	v_cndmask_b32_e32 v2, v2, v3, vcc
	v_mul_f32_e32 v2, v4, v2
	v_fmac_f32_e32 v96, v95, v2
	v_add_f32_e32 v2, v96, v66
	v_mul_f32_e32 v2, v2, v68
	v_cvt_pk_bf16_f32 v4, v2, v137
	v_lshl_add_u64 v[2:3], v[74:75], 0, s[6:7]
	global_store_short v[2:3], v4, off
	s_waitcnt lgkmcnt(0)
	s_cmpk_gt_i32 s10, 0xbff
	s_cbranch_scc0 .LBB0_91

; __device__ __forceinline__ int bidx() { int b = blockIdx.x; asm volatile("" : "+s"(b)); return b; }
; #define LAS __attribute__((address_space(3)))
; template <int PASS>
; __device__ __forceinline__ void rwkv_scan(const Params& p, int l, int wave, int lane, LAS unsigned char* lds) {
;     if (wave >= 3) return;
;     constexpr int NB = 2, NBT = 128 / NB;
;     const int G = gridDim.x; unsigned char* ws = p.ws;
;     LAS float* sb = (LAS float*)(lds + wave * 8192);
;     LAS float* cb = sb + 1024 + lane;
;     const float* ZR = (const float*)(ws + WS_ZR); const bf16_t* LR = (const bf16_t*)(ws + WS_LR);
;     const float* SIN = (const float*)(ws + WS_SIN); bf16_t* YCAT = (bf16_t*)(ws + WS_YCAT);
;     for (int u = wave * G + bidx(); u < 768; u += 3 * G) {
;         const int c = u & 31, bh = u >> 5; const int b = bh / 12, h = bh - b * 12; const int ch = h * 64 + lane;
;         const int m0 = b * SEQ + c * 128;
;         cb[0] = p.in[7][l * RWC + ch]; cb[64] = p.in[7][l * RWC + 768 + ch]; cb[128] = p.in[7][l * RWC + 1536 + ch];
; __global__ void __launch_bounds__(512, 2) mk_fwd(Params p) {
;     ...
;             } else if (s == 6 && PON(7)) {
;                 rwkv_scan<1>(p, l, wave, lane, lds);
;                 s5_scan<2>(p, l, (wave == 3) ? 0 : ((wave == 7) ? 1 : -1), 2, bidx(), gridDim.x, lane, lds + 24576);
.LBB0_313:
	v_readlane_b32 s0, v254, 17
	v_mov_b32_e32 v186, 0x600
	v_mov_b32_e32 v183, 0xc00
	v_mov_b32_e32 v198, 0x3e38aa3b
	v_mov_b32_e32 v190, 0x3727c5ac
	v_mov_b32_e32 v250, 1
	v_mov_b64_e32 v[142:143], 0x560
	s_cmp_gt_i32 s0, 2
	s_cbranch_scc1 .LBB0_324
	v_readlane_b32 s0, v253, 5
	v_readlane_b32 s1, v253, 6
	v_readlane_b32 s1, v254, 17
	s_mul_i32 s0, s1, s0
	s_mov_b32 s1, s2
	s_add_i32 s20, s1, s0
	s_cmpk_gt_i32 s20, 0x2ff
	s_cbranch_scc1 .LBB0_324
	v_readlane_b32 s0, v254, 17
	s_lshl_b32 s0, s0, 13
	v_writelane_b32 v254, s20, 39
	s_add_i32 s33, s0, 0
	v_writelane_b32 v254, s88, 40
	v_lshl_add_u32 v156, v201, 2, s33
	s_nop 0
	v_writelane_b32 v254, s89, 41
	s_setprio 2
	s_branch .LBB0_317

; __device__ __forceinline__ int bidx() { int b = blockIdx.x; asm volatile("" : "+s"(b)); return b; }
; #define LAS __attribute__((address_space(3)))
; template <int PASS>
; __device__ __forceinline__ void s5_scan(const Params& p, int l, int widx, int nw, int beff, int nblk, int lane, LAS unsigned char* lds) {
;     if (widx < 0 || widx >= nw || beff < 0) return;
;     unsigned char* ws = p.ws;
;     LAS float* ub = (LAS float*)(lds + widx * 19456);
;     LAS float* xb = ub + 512;
;     LAS float* ct = xb + 16 * 132;
;     const float* ZS = (const float*)(ws + WS_ZS); const float* tab = (const float*)(ws + WS_S5TAB + (size_t)l * SZ_S5TAB);
;     float* XE = (float*)(ws + WS_XE);
;     float* YS = (float*)(ws + WS_YS); bf16_t* YSB = (bf16_t*)(ws + WS_YSB);
;     for (int u = widx * nblk + beff; u < 1024; u += nw * nblk) {
;         const int c = u & 15, g = (u >> 4) & 31, b = u >> 9; const int gn = g * 64 + lane;
; __global__ void __launch_bounds__(512, 2) mk_fwd(Params p) {
;     ...
;                 rwkv_scan<1>(p, l, wave, lane, lds);
;                 s5_scan<2>(p, l, (wave == 3) ? 0 : ((wave == 7) ? 1 : -1), 2, bidx(), gridDim.x, lane, lds + 24576);
.LBB0_324:
	s_setprio 0
	v_readlane_b32 s1, v254, 17
	s_cmp_eq_u32 s1, 7
	s_cselect_b32 s0, 1, -1
	s_cmp_eq_u32 s1, 4
	s_cselect_b32 s0, 2, s0
	s_cmp_eq_u32 s1, 5
	s_cselect_b32 s0, 3, s0
	s_cmp_lg_u32 s1, 3
	s_cselect_b32 s0, s0, 0
	s_mov_b32 s1, s2
	s_or_b32 s4, s1, s0
	s_cmp_lt_i32 s4, 0
	v_mov_b64_e32 v[196:197], v[142:143]
	v_mov_b32_e32 v143, v190
	v_mov_b32_e32 v192, 0xfcf
	v_not_b32_e32 v193, 63
	s_cbranch_scc1 .LBB0_356
	v_readlane_b32 s4, v253, 5
	s_mul_i32 s4, s0, s4
	s_add_i32 s6, s1, s4
	s_cmpk_gt_i32 s6, 0x3ff
	v_readlane_b32 s5, v253, 6
	s_cbranch_scc1 .LBB0_356
	s_mulk_i32 s0, 0x4c00
	v_readlane_b32 s4, v255, 18
	s_add_i32 s7, s0, 0
	s_lshl_b64 s[0:1], s[86:87], 15
	v_readlane_b32 s5, v255, 19
	v_readlane_b32 s8, v253, 17
	v_lshlrev_b32_e32 v0, 2, v201
	s_lshl_b64 s[4:5], s[4:5], 2
	v_readlane_b32 s10, v253, 19
	v_or_b32_e32 v44, s0, v201
	v_mov_b32_e32 v45, s1
	v_and_b32_e32 v46, 12, v0
	v_readlane_b32 s0, v251, 40
	v_readlane_b32 s11, v253, 20
	s_add_u32 s4, s10, s4
	v_lshlrev_b32_e32 v136, 2, v46
	v_readlane_b32 s1, v251, 41
	s_addc_u32 s5, s11, s5
	v_readlane_b32 s12, v253, 21
	v_lshl_add_u64 v[48:49], s[0:1], 0, v[136:137]
	s_add_i32 s0, s7, 0x6800
	s_add_i32 s1, s7, 0x8900
	v_and_b32_e32 v134, 15, v201
	v_lshrrev_b32_e32 v135, 4, v201
	v_mul_u32_u24_e32 v138, 0x210, v134
	v_lshl_add_u32 v138, v135, 4, v138
	v_lshl_add_u32 v135, v135, 6, v134
	v_add_u32_e32 v134, s0, v138
	v_lshl_add_u32 v135, v135, 2, s0
	v_lshl_add_u32 v138, v201, 4, s0
	v_readlane_b32 s13, v253, 22
	v_readlane_b32 s14, v253, 23
	v_readlane_b32 s15, v253, 24
	v_add_u32_e32 v72, s7, v0
	v_add_u32_e32 v73, s0, v0
	v_mov_b32_e32 v0, s1
	s_movk_i32 s1, 0x210
	v_readlane_b32 s9, v253, 18
	v_lshrrev_b32_e32 v65, 2, v201
	v_mad_u32_u24 v74, v46, s1, v0
	v_mov_b32_e32 v0, s0
	v_readlane_b32 s12, v253, 41
	v_lshlrev_b32_e32 v47, 1, v201
	v_lshlrev_b32_e32 v70, 4, v201
	v_lshlrev_b32_e32 v71, 6, v65
	v_lshl_add_u64 v[50:51], s[4:5], 0, v[136:137]
	s_add_i32 s8, s7, 0x6000
	v_mad_u32_u24 v75, v65, s1, v0
	s_mov_b32 s9, s6
	v_readlane_b32 s26, v253, 55
	v_readlane_b32 s27, v253, 56
	v_readlane_b32 s13, v253, 42
	v_readlane_b32 s14, v253, 43
	v_readlane_b32 s15, v253, 44
	v_readlane_b32 s16, v253, 45
	v_readlane_b32 s17, v253, 46
	v_readlane_b32 s18, v253, 47
	v_readlane_b32 s19, v253, 48
	v_readlane_b32 s20, v253, 49
	v_readlane_b32 s21, v253, 50
	v_readlane_b32 s22, v253, 51
	v_readlane_b32 s23, v253, 52
	v_readlane_b32 s24, v253, 53
	v_readlane_b32 s25, v253, 54
	s_branch .LBB0_328

; __global__ void __launch_bounds__(512, 2) mk_fwd(Params p) {
;     ...
;         { const int sx = (ph > 0) ? (ph - 1) % NPL : -1; const bool skip = (sx == 10) || (gridDim.x == 256 && (sx == 2 || sx == 12 || sx == 15));
;           if (ph + 1 < p.ph_hi && !skip) {
;               if (ph == p.ph_lo) grid.sync();
;               else {
;                   asm volatile("s_waitcnt vmcnt(0)" ::: "memory");
;                   __syncthreads();
;                   if (threadIdx.x == 0) {
;                       unsigned* wsw = (unsigned*)p.ws; unsigned* base = wsw + 16384 + ph * 4096;
;                       const unsigned xcc = (unsigned)__builtin_amdgcn_s_getreg((3 << 11) | 20) & 0xFu;
;                       unsigned nloc = xst[0], nx = xst[1];
;                       if (nloc == 0u) {
;                           nx = 0u;
; #pragma unroll
;                           for (unsigned j = 0; j < 16; ++j) { const unsigned cj = __hip_atomic_load(wsw + 1536 + j, __ATOMIC_RELAXED, __HIP_MEMORY_SCOPE_AGENT); nx += (cj > 0u) ? 1u : 0u; nloc = (j == xcc) ? cj : nloc; }
;                           xst[0] = nloc; xst[1] = nx;
;                       }
;                       const unsigned old = __hip_atomic_fetch_add(base + xcc * 64, 1u, __ATOMIC_RELAXED, __HIP_MEMORY_SCOPE_AGENT);
;                       if (old + 1u == nloc) {
;                           __builtin_amdgcn_fence(__ATOMIC_RELEASE, "agent");
;                           asm volatile("s_waitcnt vmcnt(0)" ::: "memory");
;                           const unsigned ot = __hip_atomic_fetch_add(base + 2048, 1u, __ATOMIC_RELAXED, __HIP_MEMORY_SCOPE_AGENT);
;                           if (ot + 1u != nx) while (__hip_atomic_load(base + 2048, __ATOMIC_RELAXED, __HIP_MEMORY_SCOPE_AGENT) < nx) __builtin_amdgcn_s_sleep(1);
;                           __builtin_amdgcn_fence(__ATOMIC_ACQUIRE, "agent");
;                           __hip_atomic_fetch_add(base + 1024 + xcc * 64, 1u, __ATOMIC_RELAXED, __HIP_MEMORY_SCOPE_AGENT);
;                           asm volatile("s_waitcnt vmcnt(0)" ::: "memory");
;                       } else {
;                           while (__hip_atomic_load(base + 1024 + xcc * 64, __ATOMIC_RELAXED, __HIP_MEMORY_SCOPE_AGENT) == 0u) __builtin_amdgcn_s_sleep(1);
;                           __builtin_amdgcn_fence(__ATOMIC_ACQUIRE, "agent");
.LBB0_827:
	v_readlane_b32 s1, v254, 16
	s_cmp_lt_i32 s1, 1
	s_waitcnt lgkmcnt(0)
	s_cselect_b64 s[6:7], -1, 0
	s_add_i32 s0, s1, -1
	s_and_b32 s0, s0, 15
	s_cmp_gt_i32 s1, 0
	s_cselect_b32 s5, s0, -1
	s_cmp_eq_u32 s5, 8
	s_cbranch_scc0 .Lno_s8_seam
	s_waitcnt lgkmcnt(0)
	s_barrier
	s_mov_b32 s5, 10
.Lno_s8_seam:
	s_cmp_eq_u32 s5, 10
	v_readlane_b32 s8, v251, 32
	s_cselect_b64 s[0:1], -1, 0
	v_readlane_b32 s9, v251, 33
	s_or_b64 s[8:9], s[0:1], s[8:9]
	s_or_b64 s[6:7], s[8:9], s[6:7]
	s_and_b64 vcc, exec, s[6:7]
	s_cbranch_vccnz .LBB0_829
	s_lshr_b32 s0, 0x9004, s5
	s_bitcmp1_b32 s0, 0
	s_cselect_b64 s[0:1], -1, 0
